# v26 + in the four per-batch grid barriers the last-arriving leader no longer waits for the ack of its top-generation atomic before releasing its XCD
# baseline (speedup 1.0000x reference)
; __device__ __forceinline__ unsigned xb_ld(unsigned* p)              { return __hip_atomic_load(p, __ATOMIC_RELAXED, __HIP_MEMORY_SCOPE_AGENT); }
; __device__ __forceinline__ unsigned xb_add(unsigned* p, unsigned v) { return __hip_atomic_fetch_add(p, v, __ATOMIC_RELAXED, __HIP_MEMORY_SCOPE_AGENT); }
; #define XB_SPIN(cond, bar) do { unsigned _sp = 0; while (cond) { __builtin_amdgcn_s_sleep(1); \
;     if ((++_sp & 255u) == 0u) { if (xb_ld(&(bar)[XB_TMO])) break; if (_sp > XB_SPIN_CAP) { atomicAdd(&(bar)[XB_TMO], 1u); break; } } } } while (0)
; __device__ __forceinline__ void xcd_barrier(const int wv, const XcdBarrier& b) {
;     ...
;             __builtin_amdgcn_fence(__ATOMIC_RELEASE, "agent");
;             asm volatile("s_waitcnt vmcnt(0)" ::: "memory");
;             const unsigned og = xb_add(&bar[XB_TOP], 1u);
;             const unsigned tg = og / nx;
;             if (og + 1u == (tg + 1u) * nx) xb_add(&bar[XB_TOPGEN], 1u);
;             else XB_SPIN(xb_ld(&bar[XB_TOPGEN]) == tg, bar);
;             __builtin_amdgcn_fence(__ATOMIC_ACQUIRE, "agent");
;             xb_add(&bar[XB_XGEN(b.x)], 1u);
.LBB0_130:
	s_or_b64 exec, exec, s[2:3]
	v_add_co_u32_e32 v2, vcc, 0x2000, v2
	buffer_inv sc1
	v_addc_co_u32_e32 v3, vcc, 0, v3, vcc
	global_atomic_add v[2:3], v184, off offset:1024

; __device__ __forceinline__ unsigned xb_ld(unsigned* p)              { return __hip_atomic_load(p, __ATOMIC_RELAXED, __HIP_MEMORY_SCOPE_AGENT); }
; __device__ __forceinline__ unsigned xb_add(unsigned* p, unsigned v) { return __hip_atomic_fetch_add(p, v, __ATOMIC_RELAXED, __HIP_MEMORY_SCOPE_AGENT); }
; #define XB_SPIN(cond, bar) do { unsigned _sp = 0; while (cond) { __builtin_amdgcn_s_sleep(1); \
;     if ((++_sp & 255u) == 0u) { if (xb_ld(&(bar)[XB_TMO])) break; if (_sp > XB_SPIN_CAP) { atomicAdd(&(bar)[XB_TMO], 1u); break; } } } } while (0)
; __device__ __forceinline__ void xcd_barrier(const int wv, const XcdBarrier& b) {
;     ...
;             const unsigned og = xb_add(&bar[XB_TOP], 1u);
;             const unsigned tg = og / nx;
;             if (og + 1u == (tg + 1u) * nx) xb_add(&bar[XB_TOPGEN], 1u);
;             else XB_SPIN(xb_ld(&bar[XB_TOPGEN]) == tg, bar);
.LBB0_307:
	s_or_b64 exec, exec, s[6:7]
	s_and_saveexec_b64 s[2:3], s[8:9]
	s_cbranch_execz .LBB0_309
	global_atomic_add v[4:5], v184, off

; __device__ __forceinline__ unsigned xb_ld(unsigned* p)              { return __hip_atomic_load(p, __ATOMIC_RELAXED, __HIP_MEMORY_SCOPE_AGENT); }
; __device__ __forceinline__ unsigned xb_add(unsigned* p, unsigned v) { return __hip_atomic_fetch_add(p, v, __ATOMIC_RELAXED, __HIP_MEMORY_SCOPE_AGENT); }
; #define XB_SPIN(cond, bar) do { unsigned _sp = 0; while (cond) { __builtin_amdgcn_s_sleep(1); \
;     if ((++_sp & 255u) == 0u) { if (xb_ld(&(bar)[XB_TMO])) break; if (_sp > XB_SPIN_CAP) { atomicAdd(&(bar)[XB_TMO], 1u); break; } } } } while (0)
; __device__ __forceinline__ void xcd_barrier(const int wv, const XcdBarrier& b) {
;     ...
;             const unsigned og = xb_add(&bar[XB_TOP], 1u);
;             const unsigned tg = og / nx;
;             if (og + 1u == (tg + 1u) * nx) xb_add(&bar[XB_TOPGEN], 1u);
;             else XB_SPIN(xb_ld(&bar[XB_TOPGEN]) == tg, bar);
.LBB0_560:
	s_or_b64 exec, exec, s[6:7]
	s_and_saveexec_b64 s[2:3], s[8:9]
	s_cbranch_execz .LBB0_130
	global_atomic_add v[4:5], v184, off
	s_branch .LBB0_130
